# ph3 (token-shift + LoRA input activations): hand-written branch-free loop, 4 rows per pass with the next pass's loads in flight
# baseline (speedup 1.0000x reference)
.LBB0_417:
	s_andn2_b64 vcc, exec, s[10:11]
	s_cbranch_vccnz .LBB0_441
	s_cmp_lg_u32 s87, 3
	s_cbranch_scc1 .LBB0_441
	v_mov_b32_e32 v1, v163
	s_mov_b32 s2, s75
	v_ashrrev_i32_e32 v2, 6, v1
	s_nop 0
	v_lshl_add_u32 v6, s2, 3, v2
	v_cmp_gt_i32_e32 vcc, s83, v6
	s_and_saveexec_b64 s[10:11], vcc
	s_cbranch_execz .LBB0_440
	v_and_b32_e32 v1, 63, v1
	v_lshlrev_b32_e32 v2, 3, v1
	v_mov_b32_e32 v3, v0
	v_lshl_add_u64 v[10:11], s[66:67], 0, v[2:3]
	s_mov_b64 s[2:3], 0x18000000
	v_lshl_add_u64 v[8:9], v[10:11], 0, s[2:3]
	s_load_dwordx2 s[2:3], s[0:1], 0x30
	v_lshlrev_b32_e32 v2, 4, v1
	v_cmp_gt_u32_e64 s[40:41], 32, v1
	s_mov_b64 s[12:13], 0
	s_waitcnt lgkmcnt(0)
	v_lshl_add_u64 v[2:3], s[2:3], 0, v[2:3]
	v_add_co_u32_e32 v2, vcc, 0x1000, v2
	s_mov_b64 s[2:3], 0xa000000
	s_nop 0
	v_addc_co_u32_e32 v3, vcc, 0, v3, vcc
	global_load_dwordx4 v[2:5], v[2:3], off offset:2048
	v_cmp_lt_u32_e32 vcc, 15, v1
	v_lshl_add_u64 v[10:11], v[10:11], 0, s[2:3]
	s_and_b64 s[42:43], vcc, s[40:41]
	v_mov_b32_e32 v12, 0x4038aa3b
	v_mov_b32_e32 v13, 0xbfb8aa3b
	v_cndmask_b32_e32 v12, v12, v13, vcc
	v_mov_b32_e32 v13, -2.0
	v_mov_b32_e32 v14, 1.0
	v_cndmask_b32_e32 v13, v13, v14, vcc
	v_mov_b32_e32 v15, 0
	v_cndmask_b32_e32 v14, v14, v15, vcc
	s_movk_i32 s2, 0xe00
	s_lshl_b32 s3, s33, 2
	s_mov_b32 s12, 8
	v_mov_b32_e32 v16, v6
	v_mad_i64_i32 v[208:209], s[14:15], v16, s2, v[10:11]
	global_load_dwordx2 v[176:177], v[208:209], off offset:3072
	global_load_dwordx2 v[184:185], v[208:209], off offset:-512
	v_add_u32_e32 v16, s33, v16
	v_mad_i64_i32 v[208:209], s[14:15], v16, s2, v[10:11]
	global_load_dwordx2 v[178:179], v[208:209], off offset:3072
	global_load_dwordx2 v[186:187], v[208:209], off offset:-512
	v_add_u32_e32 v16, s33, v16
	v_mad_i64_i32 v[208:209], s[14:15], v16, s2, v[10:11]
	global_load_dwordx2 v[180:181], v[208:209], off offset:3072
	global_load_dwordx2 v[188:189], v[208:209], off offset:-512
	v_add_u32_e32 v16, s33, v16
	v_mad_i64_i32 v[208:209], s[14:15], v16, s2, v[10:11]
	global_load_dwordx2 v[182:183], v[208:209], off offset:3072
	global_load_dwordx2 v[190:191], v[208:209], off offset:-512
	s_waitcnt vmcnt(8)
.Lph3_pass0:
	v_add_u32_e32 v17, s3, v6
	v_min_u32_e32 v17, 0xffff, v17
	v_mov_b32_e32 v16, v17
	v_mad_i64_i32 v[208:209], s[14:15], v16, s2, v[10:11]
	global_load_dwordx2 v[192:193], v[208:209], off offset:3072
	global_load_dwordx2 v[200:201], v[208:209], off offset:-512
	v_add_u32_e32 v16, s33, v16
	v_mad_i64_i32 v[208:209], s[14:15], v16, s2, v[10:11]
	global_load_dwordx2 v[194:195], v[208:209], off offset:3072
	global_load_dwordx2 v[202:203], v[208:209], off offset:-512
	v_add_u32_e32 v16, s33, v16
	v_mad_i64_i32 v[208:209], s[14:15], v16, s2, v[10:11]
	global_load_dwordx2 v[196:197], v[208:209], off offset:3072
	global_load_dwordx2 v[204:205], v[208:209], off offset:-512
	v_add_u32_e32 v16, s33, v16
	v_mad_i64_i32 v[208:209], s[14:15], v16, s2, v[10:11]
	global_load_dwordx2 v[198:199], v[208:209], off offset:3072
	global_load_dwordx2 v[206:207], v[208:209], off offset:-512
	s_waitcnt vmcnt(8)
	v_mov_b32_e32 v16, v6
	v_and_b32_e32 v210, 0x7ff, v16
	v_cmp_ne_u32_e32 vcc, 0, v210
	v_lshlrev_b32_e32 v212, 16, v176
	v_and_b32_e32 v213, 0xffff0000, v176
	v_lshlrev_b32_e32 v214, 16, v177
	v_and_b32_e32 v215, 0xffff0000, v177
	v_cndmask_b32_e32 v184, 0, v184, vcc
	v_cndmask_b32_e32 v185, 0, v185, vcc
	v_lshlrev_b32_e32 v216, 16, v184
	v_and_b32_e32 v217, 0xffff0000, v184
	v_lshlrev_b32_e32 v218, 16, v185
	v_and_b32_e32 v219, 0xffff0000, v185
	v_sub_f32_e32 v216, v216, v212
	v_sub_f32_e32 v217, v217, v213
	v_sub_f32_e32 v218, v218, v214
	v_sub_f32_e32 v219, v219, v215
	v_fmac_f32_e32 v212, v2, v216
	v_fmac_f32_e32 v213, v3, v217
	v_fmac_f32_e32 v214, v4, v218
	v_fmac_f32_e32 v215, v5, v219
	v_mul_f32_e32 v216, v12, v212
	v_mul_f32_e32 v217, v12, v213
	v_mul_f32_e32 v218, v12, v214
	v_mul_f32_e32 v219, v12, v215
	v_exp_f32_e32 v216, v216
	v_exp_f32_e32 v217, v217
	v_exp_f32_e32 v218, v218
	v_exp_f32_e32 v219, v219
	v_add_f32_e32 v216, 1.0, v216
	v_add_f32_e32 v217, 1.0, v217
	v_add_f32_e32 v218, 1.0, v218
	v_add_f32_e32 v219, 1.0, v219
	v_rcp_f32_e32 v216, v216
	v_rcp_f32_e32 v217, v217
	v_rcp_f32_e32 v218, v218
	v_rcp_f32_e32 v219, v219
	v_fma_f32 v216, v216, v13, v14
	v_fma_f32 v217, v217, v13, v14
	v_fma_f32 v218, v218, v13, v14
	v_fma_f32 v219, v219, v13, v14
	v_cndmask_b32_e64 v216, v216, v212, s[42:43]
	v_cndmask_b32_e64 v217, v217, v213, s[42:43]
	v_cndmask_b32_e64 v218, v218, v214, s[42:43]
	v_cndmask_b32_e64 v219, v219, v215, s[42:43]
	v_cvt_pk_bf16_f32 v220, v216, v217
	v_cvt_pk_bf16_f32 v221, v218, v219
	v_ashrrev_i32_e32 v17, 31, v16
	v_lshlrev_b64 v[222:223], 9, v[16:17]
	v_lshl_add_u64 v[222:223], v[8:9], 0, v[222:223]
	global_store_dwordx2 v[222:223], v[220:221], off
	v_add_u32_e32 v16, s33, v16
	v_and_b32_e32 v210, 0x7ff, v16
	v_cmp_ne_u32_e32 vcc, 0, v210
	v_lshlrev_b32_e32 v212, 16, v178
	v_and_b32_e32 v213, 0xffff0000, v178
	v_lshlrev_b32_e32 v214, 16, v179
	v_and_b32_e32 v215, 0xffff0000, v179
	v_cndmask_b32_e32 v186, 0, v186, vcc
	v_cndmask_b32_e32 v187, 0, v187, vcc
	v_lshlrev_b32_e32 v216, 16, v186
	v_and_b32_e32 v217, 0xffff0000, v186
	v_lshlrev_b32_e32 v218, 16, v187
	v_and_b32_e32 v219, 0xffff0000, v187
	v_sub_f32_e32 v216, v216, v212
	v_sub_f32_e32 v217, v217, v213
	v_sub_f32_e32 v218, v218, v214
	v_sub_f32_e32 v219, v219, v215
	v_fmac_f32_e32 v212, v2, v216
	v_fmac_f32_e32 v213, v3, v217
	v_fmac_f32_e32 v214, v4, v218
	v_fmac_f32_e32 v215, v5, v219
	v_mul_f32_e32 v216, v12, v212
	v_mul_f32_e32 v217, v12, v213
	v_mul_f32_e32 v218, v12, v214
	v_mul_f32_e32 v219, v12, v215
	v_exp_f32_e32 v216, v216
	v_exp_f32_e32 v217, v217
	v_exp_f32_e32 v218, v218
	v_exp_f32_e32 v219, v219
	v_add_f32_e32 v216, 1.0, v216
	v_add_f32_e32 v217, 1.0, v217
	v_add_f32_e32 v218, 1.0, v218
	v_add_f32_e32 v219, 1.0, v219
	v_rcp_f32_e32 v216, v216
	v_rcp_f32_e32 v217, v217
	v_rcp_f32_e32 v218, v218
	v_rcp_f32_e32 v219, v219
	v_fma_f32 v216, v216, v13, v14
	v_fma_f32 v217, v217, v13, v14
	v_fma_f32 v218, v218, v13, v14
	v_fma_f32 v219, v219, v13, v14
	v_cndmask_b32_e64 v216, v216, v212, s[42:43]
	v_cndmask_b32_e64 v217, v217, v213, s[42:43]
	v_cndmask_b32_e64 v218, v218, v214, s[42:43]
	v_cndmask_b32_e64 v219, v219, v215, s[42:43]
	v_cvt_pk_bf16_f32 v220, v216, v217
	v_cvt_pk_bf16_f32 v221, v218, v219
	v_ashrrev_i32_e32 v17, 31, v16
	v_lshlrev_b64 v[222:223], 9, v[16:17]
	v_lshl_add_u64 v[222:223], v[8:9], 0, v[222:223]
	global_store_dwordx2 v[222:223], v[220:221], off
	v_add_u32_e32 v16, s33, v16
	v_and_b32_e32 v210, 0x7ff, v16
	v_cmp_ne_u32_e32 vcc, 0, v210
	v_lshlrev_b32_e32 v212, 16, v180
	v_and_b32_e32 v213, 0xffff0000, v180
	v_lshlrev_b32_e32 v214, 16, v181
	v_and_b32_e32 v215, 0xffff0000, v181
	v_cndmask_b32_e32 v188, 0, v188, vcc
	v_cndmask_b32_e32 v189, 0, v189, vcc
	v_lshlrev_b32_e32 v216, 16, v188
	v_and_b32_e32 v217, 0xffff0000, v188
	v_lshlrev_b32_e32 v218, 16, v189
	v_and_b32_e32 v219, 0xffff0000, v189
	v_sub_f32_e32 v216, v216, v212
	v_sub_f32_e32 v217, v217, v213
	v_sub_f32_e32 v218, v218, v214
	v_sub_f32_e32 v219, v219, v215
	v_fmac_f32_e32 v212, v2, v216
	v_fmac_f32_e32 v213, v3, v217
	v_fmac_f32_e32 v214, v4, v218
	v_fmac_f32_e32 v215, v5, v219
	v_mul_f32_e32 v216, v12, v212
	v_mul_f32_e32 v217, v12, v213
	v_mul_f32_e32 v218, v12, v214
	v_mul_f32_e32 v219, v12, v215
	v_exp_f32_e32 v216, v216
	v_exp_f32_e32 v217, v217
	v_exp_f32_e32 v218, v218
	v_exp_f32_e32 v219, v219
	v_add_f32_e32 v216, 1.0, v216
	v_add_f32_e32 v217, 1.0, v217
	v_add_f32_e32 v218, 1.0, v218
	v_add_f32_e32 v219, 1.0, v219
	v_rcp_f32_e32 v216, v216
	v_rcp_f32_e32 v217, v217
	v_rcp_f32_e32 v218, v218
	v_rcp_f32_e32 v219, v219
	v_fma_f32 v216, v216, v13, v14
	v_fma_f32 v217, v217, v13, v14
	v_fma_f32 v218, v218, v13, v14
	v_fma_f32 v219, v219, v13, v14
	v_cndmask_b32_e64 v216, v216, v212, s[42:43]
	v_cndmask_b32_e64 v217, v217, v213, s[42:43]
	v_cndmask_b32_e64 v218, v218, v214, s[42:43]
	v_cndmask_b32_e64 v219, v219, v215, s[42:43]
	v_cvt_pk_bf16_f32 v220, v216, v217
	v_cvt_pk_bf16_f32 v221, v218, v219
	v_ashrrev_i32_e32 v17, 31, v16
	v_lshlrev_b64 v[222:223], 9, v[16:17]
	v_lshl_add_u64 v[222:223], v[8:9], 0, v[222:223]
	global_store_dwordx2 v[222:223], v[220:221], off
	v_add_u32_e32 v16, s33, v16
	v_and_b32_e32 v210, 0x7ff, v16
	v_cmp_ne_u32_e32 vcc, 0, v210
	v_lshlrev_b32_e32 v212, 16, v182
	v_and_b32_e32 v213, 0xffff0000, v182
	v_lshlrev_b32_e32 v214, 16, v183
	v_and_b32_e32 v215, 0xffff0000, v183
	v_cndmask_b32_e32 v190, 0, v190, vcc
	v_cndmask_b32_e32 v191, 0, v191, vcc
	v_lshlrev_b32_e32 v216, 16, v190
	v_and_b32_e32 v217, 0xffff0000, v190
	v_lshlrev_b32_e32 v218, 16, v191
	v_and_b32_e32 v219, 0xffff0000, v191
	v_sub_f32_e32 v216, v216, v212
	v_sub_f32_e32 v217, v217, v213
	v_sub_f32_e32 v218, v218, v214
	v_sub_f32_e32 v219, v219, v215
	v_fmac_f32_e32 v212, v2, v216
	v_fmac_f32_e32 v213, v3, v217
	v_fmac_f32_e32 v214, v4, v218
	v_fmac_f32_e32 v215, v5, v219
	v_mul_f32_e32 v216, v12, v212
	v_mul_f32_e32 v217, v12, v213
	v_mul_f32_e32 v218, v12, v214
	v_mul_f32_e32 v219, v12, v215
	v_exp_f32_e32 v216, v216
	v_exp_f32_e32 v217, v217
	v_exp_f32_e32 v218, v218
	v_exp_f32_e32 v219, v219
	v_add_f32_e32 v216, 1.0, v216
	v_add_f32_e32 v217, 1.0, v217
	v_add_f32_e32 v218, 1.0, v218
	v_add_f32_e32 v219, 1.0, v219
	v_rcp_f32_e32 v216, v216
	v_rcp_f32_e32 v217, v217
	v_rcp_f32_e32 v218, v218
	v_rcp_f32_e32 v219, v219
	v_fma_f32 v216, v216, v13, v14
	v_fma_f32 v217, v217, v13, v14
	v_fma_f32 v218, v218, v13, v14
	v_fma_f32 v219, v219, v13, v14
	v_cndmask_b32_e64 v216, v216, v212, s[42:43]
	v_cndmask_b32_e64 v217, v217, v213, s[42:43]
	v_cndmask_b32_e64 v218, v218, v214, s[42:43]
	v_cndmask_b32_e64 v219, v219, v215, s[42:43]
	v_cvt_pk_bf16_f32 v220, v216, v217
	v_cvt_pk_bf16_f32 v221, v218, v219
	v_ashrrev_i32_e32 v17, 31, v16
	v_lshlrev_b64 v[222:223], 9, v[16:17]
	v_lshl_add_u64 v[222:223], v[8:9], 0, v[222:223]
	global_store_dwordx2 v[222:223], v[220:221], off
	v_add_u32_e32 v6, s3, v6
.Lph3_pass1:
	v_add_u32_e32 v17, s3, v6
	v_min_u32_e32 v17, 0xffff, v17
	v_mov_b32_e32 v16, v17
	v_mad_i64_i32 v[208:209], s[14:15], v16, s2, v[10:11]
	global_load_dwordx2 v[176:177], v[208:209], off offset:3072
	global_load_dwordx2 v[184:185], v[208:209], off offset:-512
	v_add_u32_e32 v16, s33, v16
	v_mad_i64_i32 v[208:209], s[14:15], v16, s2, v[10:11]
	global_load_dwordx2 v[178:179], v[208:209], off offset:3072
	global_load_dwordx2 v[186:187], v[208:209], off offset:-512
	v_add_u32_e32 v16, s33, v16
	v_mad_i64_i32 v[208:209], s[14:15], v16, s2, v[10:11]
	global_load_dwordx2 v[180:181], v[208:209], off offset:3072
	global_load_dwordx2 v[188:189], v[208:209], off offset:-512
	v_add_u32_e32 v16, s33, v16
	v_mad_i64_i32 v[208:209], s[14:15], v16, s2, v[10:11]
	global_load_dwordx2 v[182:183], v[208:209], off offset:3072
	global_load_dwordx2 v[190:191], v[208:209], off offset:-512
	s_waitcnt vmcnt(12)
	v_mov_b32_e32 v16, v6
	v_and_b32_e32 v210, 0x7ff, v16
	v_cmp_ne_u32_e32 vcc, 0, v210
	v_lshlrev_b32_e32 v212, 16, v192
	v_and_b32_e32 v213, 0xffff0000, v192
	v_lshlrev_b32_e32 v214, 16, v193
	v_and_b32_e32 v215, 0xffff0000, v193
	v_cndmask_b32_e32 v200, 0, v200, vcc
	v_cndmask_b32_e32 v201, 0, v201, vcc
	v_lshlrev_b32_e32 v216, 16, v200
	v_and_b32_e32 v217, 0xffff0000, v200
	v_lshlrev_b32_e32 v218, 16, v201
	v_and_b32_e32 v219, 0xffff0000, v201
	v_sub_f32_e32 v216, v216, v212
	v_sub_f32_e32 v217, v217, v213
	v_sub_f32_e32 v218, v218, v214
	v_sub_f32_e32 v219, v219, v215
	v_fmac_f32_e32 v212, v2, v216
	v_fmac_f32_e32 v213, v3, v217
	v_fmac_f32_e32 v214, v4, v218
	v_fmac_f32_e32 v215, v5, v219
	v_mul_f32_e32 v216, v12, v212
	v_mul_f32_e32 v217, v12, v213
	v_mul_f32_e32 v218, v12, v214
	v_mul_f32_e32 v219, v12, v215
	v_exp_f32_e32 v216, v216
	v_exp_f32_e32 v217, v217
	v_exp_f32_e32 v218, v218
	v_exp_f32_e32 v219, v219
	v_add_f32_e32 v216, 1.0, v216
	v_add_f32_e32 v217, 1.0, v217
	v_add_f32_e32 v218, 1.0, v218
	v_add_f32_e32 v219, 1.0, v219
	v_rcp_f32_e32 v216, v216
	v_rcp_f32_e32 v217, v217
	v_rcp_f32_e32 v218, v218
	v_rcp_f32_e32 v219, v219
	v_fma_f32 v216, v216, v13, v14
	v_fma_f32 v217, v217, v13, v14
	v_fma_f32 v218, v218, v13, v14
	v_fma_f32 v219, v219, v13, v14
	v_cndmask_b32_e64 v216, v216, v212, s[42:43]
	v_cndmask_b32_e64 v217, v217, v213, s[42:43]
	v_cndmask_b32_e64 v218, v218, v214, s[42:43]
	v_cndmask_b32_e64 v219, v219, v215, s[42:43]
	v_cvt_pk_bf16_f32 v220, v216, v217
	v_cvt_pk_bf16_f32 v221, v218, v219
	v_ashrrev_i32_e32 v17, 31, v16
	v_lshlrev_b64 v[222:223], 9, v[16:17]
	v_lshl_add_u64 v[222:223], v[8:9], 0, v[222:223]
	global_store_dwordx2 v[222:223], v[220:221], off
	v_add_u32_e32 v16, s33, v16
	v_and_b32_e32 v210, 0x7ff, v16
	v_cmp_ne_u32_e32 vcc, 0, v210
	v_lshlrev_b32_e32 v212, 16, v194
	v_and_b32_e32 v213, 0xffff0000, v194
	v_lshlrev_b32_e32 v214, 16, v195
	v_and_b32_e32 v215, 0xffff0000, v195
	v_cndmask_b32_e32 v202, 0, v202, vcc
	v_cndmask_b32_e32 v203, 0, v203, vcc
	v_lshlrev_b32_e32 v216, 16, v202
	v_and_b32_e32 v217, 0xffff0000, v202
	v_lshlrev_b32_e32 v218, 16, v203
	v_and_b32_e32 v219, 0xffff0000, v203
	v_sub_f32_e32 v216, v216, v212
	v_sub_f32_e32 v217, v217, v213
	v_sub_f32_e32 v218, v218, v214
	v_sub_f32_e32 v219, v219, v215
	v_fmac_f32_e32 v212, v2, v216
	v_fmac_f32_e32 v213, v3, v217
	v_fmac_f32_e32 v214, v4, v218
	v_fmac_f32_e32 v215, v5, v219
	v_mul_f32_e32 v216, v12, v212
	v_mul_f32_e32 v217, v12, v213
	v_mul_f32_e32 v218, v12, v214
	v_mul_f32_e32 v219, v12, v215
	v_exp_f32_e32 v216, v216
	v_exp_f32_e32 v217, v217
	v_exp_f32_e32 v218, v218
	v_exp_f32_e32 v219, v219
	v_add_f32_e32 v216, 1.0, v216
	v_add_f32_e32 v217, 1.0, v217
	v_add_f32_e32 v218, 1.0, v218
	v_add_f32_e32 v219, 1.0, v219
	v_rcp_f32_e32 v216, v216
	v_rcp_f32_e32 v217, v217
	v_rcp_f32_e32 v218, v218
	v_rcp_f32_e32 v219, v219
	v_fma_f32 v216, v216, v13, v14
	v_fma_f32 v217, v217, v13, v14
	v_fma_f32 v218, v218, v13, v14
	v_fma_f32 v219, v219, v13, v14
	v_cndmask_b32_e64 v216, v216, v212, s[42:43]
	v_cndmask_b32_e64 v217, v217, v213, s[42:43]
	v_cndmask_b32_e64 v218, v218, v214, s[42:43]
	v_cndmask_b32_e64 v219, v219, v215, s[42:43]
	v_cvt_pk_bf16_f32 v220, v216, v217
	v_cvt_pk_bf16_f32 v221, v218, v219
	v_ashrrev_i32_e32 v17, 31, v16
	v_lshlrev_b64 v[222:223], 9, v[16:17]
	v_lshl_add_u64 v[222:223], v[8:9], 0, v[222:223]
	global_store_dwordx2 v[222:223], v[220:221], off
	v_add_u32_e32 v16, s33, v16
	v_and_b32_e32 v210, 0x7ff, v16
	v_cmp_ne_u32_e32 vcc, 0, v210
	v_lshlrev_b32_e32 v212, 16, v196
	v_and_b32_e32 v213, 0xffff0000, v196
	v_lshlrev_b32_e32 v214, 16, v197
	v_and_b32_e32 v215, 0xffff0000, v197
	v_cndmask_b32_e32 v204, 0, v204, vcc
	v_cndmask_b32_e32 v205, 0, v205, vcc
	v_lshlrev_b32_e32 v216, 16, v204
	v_and_b32_e32 v217, 0xffff0000, v204
	v_lshlrev_b32_e32 v218, 16, v205
	v_and_b32_e32 v219, 0xffff0000, v205
	v_sub_f32_e32 v216, v216, v212
	v_sub_f32_e32 v217, v217, v213
	v_sub_f32_e32 v218, v218, v214
	v_sub_f32_e32 v219, v219, v215
	v_fmac_f32_e32 v212, v2, v216
	v_fmac_f32_e32 v213, v3, v217
	v_fmac_f32_e32 v214, v4, v218
	v_fmac_f32_e32 v215, v5, v219
	v_mul_f32_e32 v216, v12, v212
	v_mul_f32_e32 v217, v12, v213
	v_mul_f32_e32 v218, v12, v214
	v_mul_f32_e32 v219, v12, v215
	v_exp_f32_e32 v216, v216
	v_exp_f32_e32 v217, v217
	v_exp_f32_e32 v218, v218
	v_exp_f32_e32 v219, v219
	v_add_f32_e32 v216, 1.0, v216
	v_add_f32_e32 v217, 1.0, v217
	v_add_f32_e32 v218, 1.0, v218
	v_add_f32_e32 v219, 1.0, v219
	v_rcp_f32_e32 v216, v216
	v_rcp_f32_e32 v217, v217
	v_rcp_f32_e32 v218, v218
	v_rcp_f32_e32 v219, v219
	v_fma_f32 v216, v216, v13, v14
	v_fma_f32 v217, v217, v13, v14
	v_fma_f32 v218, v218, v13, v14
	v_fma_f32 v219, v219, v13, v14
	v_cndmask_b32_e64 v216, v216, v212, s[42:43]
	v_cndmask_b32_e64 v217, v217, v213, s[42:43]
	v_cndmask_b32_e64 v218, v218, v214, s[42:43]
	v_cndmask_b32_e64 v219, v219, v215, s[42:43]
	v_cvt_pk_bf16_f32 v220, v216, v217
	v_cvt_pk_bf16_f32 v221, v218, v219
	v_ashrrev_i32_e32 v17, 31, v16
	v_lshlrev_b64 v[222:223], 9, v[16:17]
	v_lshl_add_u64 v[222:223], v[8:9], 0, v[222:223]
	global_store_dwordx2 v[222:223], v[220:221], off
	v_add_u32_e32 v16, s33, v16
	v_and_b32_e32 v210, 0x7ff, v16
	v_cmp_ne_u32_e32 vcc, 0, v210
	v_lshlrev_b32_e32 v212, 16, v198
	v_and_b32_e32 v213, 0xffff0000, v198
	v_lshlrev_b32_e32 v214, 16, v199
	v_and_b32_e32 v215, 0xffff0000, v199
	v_cndmask_b32_e32 v206, 0, v206, vcc
	v_cndmask_b32_e32 v207, 0, v207, vcc
	v_lshlrev_b32_e32 v216, 16, v206
	v_and_b32_e32 v217, 0xffff0000, v206
	v_lshlrev_b32_e32 v218, 16, v207
	v_and_b32_e32 v219, 0xffff0000, v207
	v_sub_f32_e32 v216, v216, v212
	v_sub_f32_e32 v217, v217, v213
	v_sub_f32_e32 v218, v218, v214
	v_sub_f32_e32 v219, v219, v215
	v_fmac_f32_e32 v212, v2, v216
	v_fmac_f32_e32 v213, v3, v217
	v_fmac_f32_e32 v214, v4, v218
	v_fmac_f32_e32 v215, v5, v219
	v_mul_f32_e32 v216, v12, v212
	v_mul_f32_e32 v217, v12, v213
	v_mul_f32_e32 v218, v12, v214
	v_mul_f32_e32 v219, v12, v215
	v_exp_f32_e32 v216, v216
	v_exp_f32_e32 v217, v217
	v_exp_f32_e32 v218, v218
	v_exp_f32_e32 v219, v219
	v_add_f32_e32 v216, 1.0, v216
	v_add_f32_e32 v217, 1.0, v217
	v_add_f32_e32 v218, 1.0, v218
	v_add_f32_e32 v219, 1.0, v219
	v_rcp_f32_e32 v216, v216
	v_rcp_f32_e32 v217, v217
	v_rcp_f32_e32 v218, v218
	v_rcp_f32_e32 v219, v219
	v_fma_f32 v216, v216, v13, v14
	v_fma_f32 v217, v217, v13, v14
	v_fma_f32 v218, v218, v13, v14
	v_fma_f32 v219, v219, v13, v14
	v_cndmask_b32_e64 v216, v216, v212, s[42:43]
	v_cndmask_b32_e64 v217, v217, v213, s[42:43]
	v_cndmask_b32_e64 v218, v218, v214, s[42:43]
	v_cndmask_b32_e64 v219, v219, v215, s[42:43]
	v_cvt_pk_bf16_f32 v220, v216, v217
	v_cvt_pk_bf16_f32 v221, v218, v219
	v_ashrrev_i32_e32 v17, 31, v16
	v_lshlrev_b64 v[222:223], 9, v[16:17]
	v_lshl_add_u64 v[222:223], v[8:9], 0, v[222:223]
	global_store_dwordx2 v[222:223], v[220:221], off
	v_add_u32_e32 v6, s3, v6
	s_sub_u32 s12, s12, 2
	s_cmp_lg_u32 s12, 0
	s_cbranch_scc1 .Lph3_pass0
	s_waitcnt vmcnt(0)
